# gmlp phase: weight/LN/GU loads batched up front instead of load-wait per step
# baseline (speedup 1.0000x reference)
; #define LAS __attribute__((address_space(3)))
; DI float bflo(unsigned w) { return __uint_as_float(w << 16); }
; DI float bfhi(unsigned w) { return __uint_as_float(w & 0xffff0000u); }
; DI unsigned short f2bf(float f) { return (unsigned short)(cvtpk(f, 0.f) & 0xffffu); }
; DI void gmlp_phase(unsigned char* sl, const float* ln_g, const float* ln_b, const float* ws_, const float* bs_, bool skipctx, LAS unsigned char* lds) {
;     ...
;         __syncthreads();
;         if (tid < 128) { const f32x4* pp_ = (const f32x4*)((const float*)(sl + 5 * SLAB) + (r0 + tid) * 32); float sm = 0.f, sq = 0.f;
; #pragma unroll
;             for (int i = 0; i < 8; ++i) { const f32x4 v = pp_[i]; sm += v[0] + v[2]; sq += v[1] + v[3]; }
;             const float mu = sm * (1.f / 1024.f); const float var = fmaxf(sq * (1.f / 1024.f) - mu * mu, 0.f);
;             stat[2 * tid] = mu; stat[2 * tid + 1] = rsqrtf(var + EPS); }
;         __syncthreads();
;         { const int s = tid >> 2, qd = tid & 3; const bf16_t* rp = GV + (r0 + s) * D + g * 128 + qd * 32; const float mu = stat[2 * s], rs = stat[2 * s + 1];
; #pragma unroll
;           for (int i = 0; i < 4; ++i) { const u32x4 w = *(const u32x4*)(rp + 8 * i);
;               const int cb_ = g * 128 + qd * 32 + 8 * i; const f32x4 lg0 = *(const f32x4*)(ln_g + cb_), lg1 = *(const f32x4*)(ln_g + cb_ + 4), lb0 = *(const f32x4*)(ln_b + cb_), lb1 = *(const f32x4*)(ln_b + cb_ + 4);
; #pragma unroll
;               for (int e = 0; e < 4; ++e) { const int c = qd * 32 + 8 * i + 2 * e;
;                   const float ga = (e < 2) ? lg0[2 * e] : lg1[2 * e - 4], gb = (e < 2) ? lg0[2 * e + 1] : lg1[2 * e - 3], ba = (e < 2) ? lb0[2 * e] : lb1[2 * e - 4], bb = (e < 2) ? lb0[2 * e + 1] : lb1[2 * e - 3];
;                   const float v0 = (bflo(w[e]) - mu) * rs * ga + ba, v1 = (bfhi(w[e]) - mu) * rs * gb + bb;
;                   *(LAS unsigned short*)(lds + c * 272 + s * 2) = f2bf(v0); *(LAS unsigned short*)(lds + (c + 1) * 272 + s * 2) = f2bf(v1); } } }
;     ...
;         const float* wrow = ws_ + ((size_t)g * 128 + 32 * tb + r32) * 128 + 8 * hh;
; #pragma unroll
;         for (int s = 0; s < 8; ++s) { const f32x4 w0 = *(const f32x4*)(wrow + 16 * s), w1 = *(const f32x4*)(wrow + 16 * s + 4);
.LBB0_722:
	s_or_b64 exec, exec, s[56:57]
	v_lshl_add_u64 v[2:3], s[58:59], 0, v[36:37]
	v_lshlrev_b64 v[2:3], 11, v[2:3]
	s_and_b32 s92, s60, 0x380
	v_lshl_add_u64 v[2:3], s[52:53], 0, v[2:3]
	s_lshl_b32 s56, s92, 1
	s_mov_b32 s57, s93
	v_lshl_add_u64 v[2:3], v[2:3], 0, s[56:57]
	v_lshlrev_b32_e32 v4, 1, v38
	v_mov_b32_e32 v5, v0
	v_lshl_add_u64 v[12:13], v[2:3], 0, v[4:5]
	s_waitcnt lgkmcnt(0)
	s_barrier
	v_or_b32_e32 v2, s92, v38
	v_lshlrev_b32_e32 v2, 2, v2
	v_mov_b32_e32 v3, v0
	v_lshl_add_u64 v[16:17], s[42:43], 0, v[2:3]
	v_lshl_add_u64 v[14:15], s[44:45], 0, v[2:3]
	ds_read_b64 v[10:11], v1 offset:40960
	v_lshl_add_u64 v[134:135], v[40:41], 0, s[92:93]
	v_lshlrev_b64 v[134:135], 9, v[134:135]
	v_lshl_add_u64 v[134:135], v[42:43], 0, v[134:135]
	flat_load_dwordx4 v[70:73], v[134:135]
	flat_load_dwordx4 v[74:77], v[134:135] offset:16
	flat_load_dwordx4 v[78:81], v[134:135] offset:64
	flat_load_dwordx4 v[82:85], v[134:135] offset:80
	flat_load_dwordx4 v[86:89], v[134:135] offset:128
	flat_load_dwordx4 v[90:93], v[134:135] offset:144
	flat_load_dwordx4 v[94:97], v[134:135] offset:192
	flat_load_dwordx4 v[98:101], v[134:135] offset:208
	flat_load_dwordx4 v[102:105], v[134:135] offset:256
	flat_load_dwordx4 v[106:109], v[134:135] offset:272
	flat_load_dwordx4 v[110:113], v[134:135] offset:320
	flat_load_dwordx4 v[114:117], v[134:135] offset:336
	flat_load_dwordx4 v[118:121], v[134:135] offset:384
	flat_load_dwordx4 v[122:125], v[134:135] offset:400
	flat_load_dwordx4 v[126:129], v[134:135] offset:448
	flat_load_dwordx4 v[130:133], v[134:135] offset:464
	flat_load_dwordx4 v[18:21], v[12:13]
	flat_load_dwordx4 v[22:25], v[16:17]
	flat_load_dwordx4 v[6:9], v[16:17] offset:16
	flat_load_dwordx4 v[26:29], v[14:15]
	flat_load_dwordx4 v[2:5], v[14:15] offset:16
	flat_load_dwordx4 v[144:147], v[12:13] offset:16
	flat_load_dwordx4 v[148:151], v[16:17] offset:32
	flat_load_dwordx4 v[140:143], v[16:17] offset:48
	flat_load_dwordx4 v[152:155], v[14:15] offset:32
	flat_load_dwordx4 v[136:139], v[14:15] offset:48
	flat_load_dwordx4 v[220:223], v[12:13] offset:32
	flat_load_dwordx4 v[224:227], v[16:17] offset:64
	flat_load_dwordx4 v[216:219], v[16:17] offset:80
	flat_load_dwordx4 v[228:231], v[14:15] offset:64
	flat_load_dwordx4 v[212:215], v[14:15] offset:80
	flat_load_dwordx4 v[166:169], v[12:13] offset:48
	flat_load_dwordx4 v[170:173], v[16:17] offset:96
	flat_load_dwordx4 v[190:193], v[16:17] offset:112
	flat_load_dwordx4 v[194:197], v[14:15] offset:96
	flat_load_dwordx4 v[174:177], v[14:15] offset:112
	s_waitcnt vmcnt(0) lgkmcnt(0)
	v_lshlrev_b32_e32 v30, 16, v18
	v_and_b32_e32 v18, 0xffff0000, v18
	v_sub_f32_e32 v18, v18, v10
	v_mul_f32_e32 v18, v11, v18
	v_sub_f32_e32 v30, v30, v10
	v_mul_f32_e32 v30, v11, v30
	v_fma_f32 v18, v23, v18, v27
	v_cvt_pk_bf16_f32 v18, v18, s0
	ds_write_b16 v47, v18 offset:272
	v_lshlrev_b32_e32 v18, 16, v19
	v_sub_f32_e32 v18, v18, v10
	v_and_b32_e32 v19, 0xffff0000, v19
	v_mul_f32_e32 v18, v11, v18
	v_sub_f32_e32 v19, v19, v10
	v_fma_f32 v18, v24, v18, v28
	v_mul_f32_e32 v19, v11, v19
	v_fmac_f32_e32 v29, v25, v19
	v_cvt_pk_bf16_f32 v18, v18, s0
	ds_write_b16 v47, v18 offset:544
	v_cvt_pk_bf16_f32 v18, v29, s0
	ds_write_b16 v47, v18 offset:816
	v_lshlrev_b32_e32 v18, 16, v20
	v_sub_f32_e32 v18, v18, v10
	v_mul_f32_e32 v18, v11, v18
	v_fma_f32 v2, v6, v18, v2
	v_and_b32_e32 v6, 0xffff0000, v20
	v_sub_f32_e32 v6, v6, v10
	v_mul_f32_e32 v6, v11, v6
	v_fma_f32 v3, v7, v6, v3
	v_cvt_pk_bf16_f32 v2, v2, s0
	ds_write_b16 v47, v2 offset:1088
	v_cvt_pk_bf16_f32 v2, v3, s0
	ds_write_b16 v47, v2 offset:1360
	v_lshlrev_b32_e32 v2, 16, v21
	v_sub_f32_e32 v2, v2, v10
	v_and_b32_e32 v3, 0xffff0000, v21
	v_mul_f32_e32 v2, v11, v2
	v_sub_f32_e32 v3, v3, v10
	v_fma_f32 v2, v8, v2, v4
	v_mul_f32_e32 v3, v11, v3
	v_fma_f32 v22, v22, v30, v26
	v_fmac_f32_e32 v5, v9, v3
	v_cvt_pk_bf16_f32 v2, v2, s0
	v_cvt_pk_bf16_f32 v22, v22, s0
	ds_write_b16 v47, v2 offset:1632
	v_cvt_pk_bf16_f32 v2, v5, s0
	ds_write_b16 v47, v22
	ds_write_b16 v47, v2 offset:1904
	v_lshlrev_b32_e32 v156, 16, v144
	v_and_b32_e32 v144, 0xffff0000, v144
	v_sub_f32_e32 v144, v144, v10
	v_mul_f32_e32 v144, v11, v144
	v_fma_f32 v144, v149, v144, v153
	v_cvt_pk_bf16_f32 v144, v144, s0
	ds_write_b16 v47, v144 offset:2448
	v_lshlrev_b32_e32 v144, 16, v145
	v_sub_f32_e32 v144, v144, v10
	v_and_b32_e32 v145, 0xffff0000, v145
	v_mul_f32_e32 v144, v11, v144
	v_sub_f32_e32 v145, v145, v10
	v_fma_f32 v144, v150, v144, v154
	v_mul_f32_e32 v145, v11, v145
	v_fmac_f32_e32 v155, v151, v145
	v_cvt_pk_bf16_f32 v144, v144, s0
	ds_write_b16 v47, v144 offset:2720
	v_cvt_pk_bf16_f32 v144, v155, s0
	ds_write_b16 v47, v144 offset:2992
	v_lshlrev_b32_e32 v144, 16, v146
	v_sub_f32_e32 v144, v144, v10
	v_mul_f32_e32 v144, v11, v144
	v_fma_f32 v136, v140, v144, v136
	v_and_b32_e32 v140, 0xffff0000, v146
	v_sub_f32_e32 v140, v140, v10
	v_mul_f32_e32 v140, v11, v140
	v_fma_f32 v137, v141, v140, v137
	v_cvt_pk_bf16_f32 v136, v136, s0
	ds_write_b16 v47, v136 offset:3264
	v_cvt_pk_bf16_f32 v136, v137, s0
	ds_write_b16 v47, v136 offset:3536
	v_lshlrev_b32_e32 v136, 16, v147
	v_sub_f32_e32 v136, v136, v10
	v_and_b32_e32 v137, 0xffff0000, v147
	v_sub_f32_e32 v156, v156, v10
	v_mul_f32_e32 v136, v11, v136
	v_sub_f32_e32 v137, v137, v10
	v_mul_f32_e32 v156, v11, v156
	v_fma_f32 v136, v142, v136, v138
	v_mul_f32_e32 v137, v11, v137
	v_fma_f32 v148, v148, v156, v152
	v_fmac_f32_e32 v139, v143, v137
	v_cvt_pk_bf16_f32 v136, v136, s0
	v_cvt_pk_bf16_f32 v148, v148, s0
	ds_write_b16 v47, v136 offset:3808
	v_cvt_pk_bf16_f32 v136, v139, s0
	ds_write_b16 v47, v148 offset:2176
	ds_write_b16 v47, v136 offset:4080
; #define LAS __attribute__((address_space(3)))
; DI unsigned cvtpk(float lo, float hi) { f32x2_t v = {lo, hi}; bf16x2_t b = __builtin_convertvector(v, bf16x2_t); return __builtin_bit_cast(unsigned, b); }
; DI float bflo(unsigned w) { return __uint_as_float(w << 16); }
; DI float bfhi(unsigned w) { return __uint_as_float(w & 0xffff0000u); }
; DI unsigned short f2bf(float f) { return (unsigned short)(cvtpk(f, 0.f) & 0xffffu); }
; #define MFMA32(a, b, c) __builtin_amdgcn_mfma_f32_32x32x16_bf16((a), (b), (c), 0, 0, 0)
; DI void gmlp_phase(unsigned char* sl, const float* ln_g, const float* ln_b, const float* ws_, const float* bs_, bool skipctx, LAS unsigned char* lds) {
;     ...
;           for (int i = 0; i < 4; ++i) { const u32x4 w = *(const u32x4*)(rp + 8 * i);
;               const int cb_ = g * 128 + qd * 32 + 8 * i; const f32x4 lg0 = *(const f32x4*)(ln_g + cb_), lg1 = *(const f32x4*)(ln_g + cb_ + 4), lb0 = *(const f32x4*)(ln_b + cb_), lb1 = *(const f32x4*)(ln_b + cb_ + 4);
; #pragma unroll
;               for (int e = 0; e < 4; ++e) { const int c = qd * 32 + 8 * i + 2 * e;
;                   const float ga = (e < 2) ? lg0[2 * e] : lg1[2 * e - 4], gb = (e < 2) ? lg0[2 * e + 1] : lg1[2 * e - 3], ba = (e < 2) ? lb0[2 * e] : lb1[2 * e - 4], bb = (e < 2) ? lb0[2 * e + 1] : lb1[2 * e - 3];
;                   const float v0 = (bflo(w[e]) - mu) * rs * ga + ba, v1 = (bfhi(w[e]) - mu) * rs * gb + bb;
;                   *(LAS unsigned short*)(lds + c * 272 + s * 2) = f2bf(v0); *(LAS unsigned short*)(lds + (c + 1) * 272 + s * 2) = f2bf(v1); } } }
;     ...
;         for (int s = 0; s < 8; ++s) { const f32x4 w0 = *(const f32x4*)(wrow + 16 * s), w1 = *(const f32x4*)(wrow + 16 * s + 4);
;             u32x4 pa; pa.x = cvtpk(w0[0], w0[1]); pa.y = cvtpk(w0[2], w0[3]); pa.z = cvtpk(w1[0], w1[1]); pa.w = cvtpk(w1[2], w1[3]);
;             const bf16x8 af = __builtin_bit_cast(bf16x8, pa);
; #pragma unroll
;             for (int t = 0; t < 2; ++t) { const bf16x8 bfv = *(const LAS bf16x8*)(lds + (32 * (cb0 + t) + r32) * 272 + (16 * s + 8 * hh) * 2); acc[t] = MFMA32(bfv, af, acc[t]); } }
	v_lshlrev_b32_e32 v232, 16, v220
	v_and_b32_e32 v220, 0xffff0000, v220
	v_sub_f32_e32 v220, v220, v10
	v_mul_f32_e32 v220, v11, v220
	v_fma_f32 v220, v225, v220, v229
	v_cvt_pk_bf16_f32 v220, v220, s0
	ds_write_b16 v47, v220 offset:4624
	v_lshlrev_b32_e32 v220, 16, v221
	v_sub_f32_e32 v220, v220, v10
	v_and_b32_e32 v221, 0xffff0000, v221
	v_mul_f32_e32 v220, v11, v220
	v_sub_f32_e32 v221, v221, v10
	v_fma_f32 v220, v226, v220, v230
	v_mul_f32_e32 v221, v11, v221
	v_fmac_f32_e32 v231, v227, v221
	v_cvt_pk_bf16_f32 v220, v220, s0
	ds_write_b16 v47, v220 offset:4896
	v_cvt_pk_bf16_f32 v220, v231, s0
	ds_write_b16 v47, v220 offset:5168
	v_lshlrev_b32_e32 v220, 16, v222
	v_sub_f32_e32 v220, v220, v10
	v_mul_f32_e32 v220, v11, v220
	v_fma_f32 v212, v216, v220, v212
	v_and_b32_e32 v216, 0xffff0000, v222
	v_sub_f32_e32 v216, v216, v10
	v_mul_f32_e32 v216, v11, v216
	v_fma_f32 v213, v217, v216, v213
	v_cvt_pk_bf16_f32 v212, v212, s0
	ds_write_b16 v47, v212 offset:5440
	v_cvt_pk_bf16_f32 v212, v213, s0
	ds_write_b16 v47, v212 offset:5712
	v_lshlrev_b32_e32 v212, 16, v223
	v_sub_f32_e32 v212, v212, v10
	v_and_b32_e32 v213, 0xffff0000, v223
	v_sub_f32_e32 v232, v232, v10
	v_mul_f32_e32 v212, v11, v212
	v_sub_f32_e32 v213, v213, v10
	v_mul_f32_e32 v232, v11, v232
	v_fma_f32 v212, v218, v212, v214
	v_mul_f32_e32 v213, v11, v213
	v_fma_f32 v224, v224, v232, v228
	v_fmac_f32_e32 v215, v219, v213
	v_cvt_pk_bf16_f32 v212, v212, s0
	v_cvt_pk_bf16_f32 v224, v224, s0
	ds_write_b16 v47, v212 offset:5984
	v_cvt_pk_bf16_f32 v212, v215, s0
	ds_write_b16 v47, v224 offset:4352
	ds_write_b16 v47, v212 offset:6256
	v_lshlrev_b32_e32 v198, 16, v166
	v_and_b32_e32 v166, 0xffff0000, v166
	v_sub_f32_e32 v166, v166, v10
	v_mul_f32_e32 v166, v11, v166
	v_fma_f32 v166, v171, v166, v195
	v_cvt_pk_bf16_f32 v166, v166, s0
	ds_write_b16 v47, v166 offset:6800
	v_lshlrev_b32_e32 v166, 16, v167
	v_sub_f32_e32 v166, v166, v10
	v_and_b32_e32 v167, 0xffff0000, v167
	v_mul_f32_e32 v166, v11, v166
	v_sub_f32_e32 v167, v167, v10
	v_fma_f32 v166, v172, v166, v196
	v_mul_f32_e32 v167, v11, v167
	v_fmac_f32_e32 v197, v173, v167
	v_cvt_pk_bf16_f32 v166, v166, s0
	ds_write_b16 v47, v166 offset:7072
	v_cvt_pk_bf16_f32 v166, v197, s0
	ds_write_b16 v47, v166 offset:7344
	v_lshlrev_b32_e32 v166, 16, v168
	v_sub_f32_e32 v166, v166, v10
	v_and_b32_e32 v167, 0xffff0000, v168
	v_mul_f32_e32 v166, v11, v166
	v_sub_f32_e32 v167, v167, v10
	v_fma_f32 v166, v190, v166, v174
	v_mul_f32_e32 v167, v11, v167
	v_fma_f32 v167, v191, v167, v175
	v_cvt_pk_bf16_f32 v166, v166, s0
	ds_write_b16 v47, v166 offset:7616
	v_cvt_pk_bf16_f32 v166, v167, s0
	ds_write_b16 v47, v166 offset:7888
	v_lshlrev_b32_e32 v166, 16, v169
	v_sub_f32_e32 v166, v166, v10
	v_and_b32_e32 v167, 0xffff0000, v169
	v_mul_f32_e32 v166, v11, v166
	v_sub_f32_e32 v167, v167, v10
	v_fma_f32 v166, v192, v166, v176
	v_mul_f32_e32 v167, v11, v167
	v_fmac_f32_e32 v177, v193, v167
	v_cvt_pk_bf16_f32 v166, v166, s0
	v_sub_f32_e32 v198, v198, v10
	ds_write_b16 v47, v166 offset:8160
	v_cvt_pk_bf16_f32 v166, v177, s0
	v_mul_f32_e32 v198, v11, v198
	ds_write_b16 v47, v166 offset:8432
	v_lshl_add_u64 v[166:167], v[40:41], 0, s[92:93]
	v_fma_f32 v170, v170, v198, v194
	v_lshlrev_b64 v[166:167], 9, v[166:167]
	v_cvt_pk_bf16_f32 v170, v170, s0
	v_lshl_add_u64 v[48:49], v[42:43], 0, v[166:167]
	ds_write_b16 v47, v170 offset:6528
	s_waitcnt lgkmcnt(0)
	s_barrier
	s_waitcnt vmcnt(0) lgkmcnt(0)
	v_cvt_pk_bf16_f32 v2, v70, v71
	v_cvt_pk_bf16_f32 v3, v72, v73
	v_cvt_pk_bf16_f32 v4, v74, v75
	v_cvt_pk_bf16_f32 v5, v76, v77
	ds_read_b128 v[6:9], v52
	ds_read_b128 v[54:57], v52 offset:32
	s_waitcnt lgkmcnt(1)
	v_mfma_f32_32x32x16_bf16 v[18:33], v[6:9], v[2:5], 0
	ds_read_b128 v[6:9], v53
	ds_read_b128 v[58:61], v53 offset:32
	s_waitcnt vmcnt(0) lgkmcnt(0)
	v_cvt_pk_bf16_f32 v62, v78, v79
	v_mfma_f32_32x32x16_bf16 v[2:17], v[6:9], v[2:5], 0
	v_cvt_pk_bf16_f32 v63, v80, v81
	v_cvt_pk_bf16_f32 v64, v82, v83
	v_cvt_pk_bf16_f32 v65, v84, v85
	s_nop 1
	v_mfma_f32_32x32x16_bf16 v[18:33], v[54:57], v[62:65], v[18:33]
	v_mfma_f32_32x32x16_bf16 v[2:17], v[58:61], v[62:65], v[2:17]
	s_waitcnt vmcnt(0) lgkmcnt(0)
	v_cvt_pk_bf16_f32 v54, v86, v87
	v_cvt_pk_bf16_f32 v55, v88, v89
	v_cvt_pk_bf16_f32 v56, v90, v91
	v_cvt_pk_bf16_f32 v57, v92, v93
	ds_read_b128 v[58:61], v52 offset:64
	s_waitcnt lgkmcnt(0)
	v_mfma_f32_32x32x16_bf16 v[18:33], v[58:61], v[54:57], v[18:33]
	ds_read_b128 v[58:61], v53 offset:64
	s_waitcnt lgkmcnt(0)
	v_mfma_f32_32x32x16_bf16 v[2:17], v[58:61], v[54:57], v[2:17]
	s_waitcnt vmcnt(0) lgkmcnt(0)
	v_cvt_pk_bf16_f32 v54, v94, v95
	v_cvt_pk_bf16_f32 v55, v96, v97
	v_cvt_pk_bf16_f32 v56, v98, v99
	v_cvt_pk_bf16_f32 v57, v100, v101
	ds_read_b128 v[58:61], v52 offset:96
	s_waitcnt lgkmcnt(0)
	v_mfma_f32_32x32x16_bf16 v[18:33], v[58:61], v[54:57], v[18:33]
	ds_read_b128 v[58:61], v53 offset:96
	s_waitcnt lgkmcnt(0)
	v_mfma_f32_32x32x16_bf16 v[2:17], v[58:61], v[54:57], v[2:17]
	s_waitcnt vmcnt(0) lgkmcnt(0)
	v_cvt_pk_bf16_f32 v54, v102, v103
	v_cvt_pk_bf16_f32 v55, v104, v105
	v_cvt_pk_bf16_f32 v56, v106, v107
	v_cvt_pk_bf16_f32 v57, v108, v109
	ds_read_b128 v[58:61], v52 offset:128
	s_waitcnt lgkmcnt(0)
	v_mfma_f32_32x32x16_bf16 v[18:33], v[58:61], v[54:57], v[18:33]
	ds_read_b128 v[58:61], v53 offset:128
	s_waitcnt lgkmcnt(0)
	v_mfma_f32_32x32x16_bf16 v[2:17], v[58:61], v[54:57], v[2:17]
	s_waitcnt vmcnt(0) lgkmcnt(0)
	v_cvt_pk_bf16_f32 v54, v110, v111
	v_cvt_pk_bf16_f32 v55, v112, v113
	v_cvt_pk_bf16_f32 v56, v114, v115
	v_cvt_pk_bf16_f32 v57, v116, v117
	ds_read_b128 v[58:61], v52 offset:160
	s_waitcnt lgkmcnt(0)
; #define LAS __attribute__((address_space(3)))
; DI unsigned cvtpk(float lo, float hi) { f32x2_t v = {lo, hi}; bf16x2_t b = __builtin_convertvector(v, bf16x2_t); return __builtin_bit_cast(unsigned, b); }
; DI float bflo(unsigned w) { return __uint_as_float(w << 16); }
; DI float bfhi(unsigned w) { return __uint_as_float(w & 0xffff0000u); }
; #define MFMA32(a, b, c) __builtin_amdgcn_mfma_f32_32x32x16_bf16((a), (b), (c), 0, 0, 0)
; DI void gmlp_phase(unsigned char* sl, const float* ln_g, const float* ln_b, const float* ws_, const float* bs_, bool skipctx, LAS unsigned char* lds) {
;     ...
;         for (int s = 0; s < 8; ++s) { const f32x4 w0 = *(const f32x4*)(wrow + 16 * s), w1 = *(const f32x4*)(wrow + 16 * s + 4);
;             u32x4 pa; pa.x = cvtpk(w0[0], w0[1]); pa.y = cvtpk(w0[2], w0[3]); pa.z = cvtpk(w1[0], w1[1]); pa.w = cvtpk(w1[2], w1[3]);
;             const bf16x8 af = __builtin_bit_cast(bf16x8, pa);
; #pragma unroll
;             for (int t = 0; t < 2; ++t) { const bf16x8 bfv = *(const LAS bf16x8*)(lds + (32 * (cb0 + t) + r32) * 272 + (16 * s + 8 * hh) * 2); acc[t] = MFMA32(bfv, af, acc[t]); } }
;         { const int tt = 32 * tb + r32; const float bias = bs_[g * 128 + tt];
; #pragma unroll
;           for (int t = 0; t < 2; ++t)
; #pragma unroll
;             for (int g4 = 0; g4 < 4; ++g4) { const size_t off = (r0 + tt) * D + g * 128 + 32 * (cb0 + t) + 8 * g4 + 4 * hh;
;                 const u32x2 gu = *(const u32x2*)(GU + off);
;                 u32x2 w; w.x = cvtpk(bflo(gu.x) * (acc[t][4 * g4] + bias), bfhi(gu.x) * (acc[t][4 * g4 + 1] + bias)); w.y = cvtpk(bflo(gu.y) * (acc[t][4 * g4 + 2] + bias), bfhi(gu.y) * (acc[t][4 * g4 + 3] + bias));
;                 *(u32x2*)(GU + off) = w; } }
	v_mfma_f32_32x32x16_bf16 v[18:33], v[58:61], v[54:57], v[18:33]
	ds_read_b128 v[58:61], v53 offset:160
	s_waitcnt lgkmcnt(0)
	v_mfma_f32_32x32x16_bf16 v[2:17], v[58:61], v[54:57], v[2:17]
	s_waitcnt vmcnt(0) lgkmcnt(0)
	v_cvt_pk_bf16_f32 v54, v118, v119
	v_cvt_pk_bf16_f32 v55, v120, v121
	v_cvt_pk_bf16_f32 v56, v122, v123
	v_cvt_pk_bf16_f32 v57, v124, v125
	ds_read_b128 v[58:61], v52 offset:192
	s_waitcnt lgkmcnt(0)
	v_mfma_f32_32x32x16_bf16 v[18:33], v[58:61], v[54:57], v[18:33]
	ds_read_b128 v[58:61], v53 offset:192
	s_waitcnt lgkmcnt(0)
	v_mfma_f32_32x32x16_bf16 v[2:17], v[58:61], v[54:57], v[2:17]
	s_nop 0
	s_waitcnt vmcnt(0) lgkmcnt(0)
	v_cvt_pk_bf16_f32 v54, v126, v127
	v_cvt_pk_bf16_f32 v55, v128, v129
	v_cvt_pk_bf16_f32 v56, v130, v131
	v_cvt_pk_bf16_f32 v57, v132, v133
	ds_read_b128 v[48:51], v52 offset:224
	s_waitcnt lgkmcnt(0)
	v_mfma_f32_32x32x16_bf16 v[18:33], v[48:51], v[54:57], v[18:33]
	ds_read_b128 v[48:51], v53 offset:224
	s_waitcnt lgkmcnt(0)
	v_mfma_f32_32x32x16_bf16 v[2:17], v[48:51], v[54:57], v[2:17]
	v_add_u32_e32 v48, s92, v44
	v_ashrrev_i32_e32 v49, 31, v48
	v_lshl_add_u64 v[50:51], s[58:59], 0, v[44:45]
	v_lshl_add_u64 v[48:49], v[48:49], 2, s[48:49]
	v_lshlrev_b64 v[50:51], 10, v[50:51]
	flat_load_dword v48, v[48:49]
	v_or_b32_e32 v49, v50, v46
	v_or_b32_e32 v50, s46, v49
	v_lshl_add_u64 v[54:55], v[50:51], 1, s[50:51]
	v_lshl_add_u64 v[54:55], v[54:55], 0, s[56:57]
	v_or_b32_e32 v136, s47, v49
	v_mov_b32_e32 v137, v51
	s_add_u32 s56, s50, s56
	s_addc_u32 s57, s51, 0
	v_lshl_add_u64 v[138:139], v[136:137], 1, s[56:57]
	flat_load_dwordx2 v[140:141], v[54:55]
	flat_load_dwordx2 v[142:143], v[54:55] offset:16
	flat_load_dwordx2 v[144:145], v[54:55] offset:32
	flat_load_dwordx2 v[146:147], v[54:55] offset:48
	flat_load_dwordx2 v[148:149], v[138:139]
	flat_load_dwordx2 v[150:151], v[138:139] offset:16
	flat_load_dwordx2 v[152:153], v[138:139] offset:32
	flat_load_dwordx2 v[154:155], v[138:139] offset:48
	s_waitcnt vmcnt(0) lgkmcnt(0)
	v_pk_add_f32 v[156:157], v[18:19], v[48:49] op_sel_hi:[1,0]
	v_pk_add_f32 v[158:159], v[20:21], v[48:49] op_sel_hi:[1,0]
	v_lshlrev_b32_e32 v160, 16, v140
	v_and_b32_e32 v161, 0xffff0000, v140
	v_lshlrev_b32_e32 v162, 16, v141
	v_and_b32_e32 v163, 0xffff0000, v141
	v_pk_mul_f32 v[156:157], v[156:157], v[160:161]
	v_pk_mul_f32 v[158:159], v[158:159], v[162:163]
	s_nop 0
	v_cvt_pk_bf16_f32 v164, v156, v157
	v_cvt_pk_bf16_f32 v165, v158, v159
	flat_store_dwordx2 v[54:55], v[164:165]
	v_pk_add_f32 v[156:157], v[22:23], v[48:49] op_sel_hi:[1,0]
	v_pk_add_f32 v[158:159], v[24:25], v[48:49] op_sel_hi:[1,0]
	v_lshlrev_b32_e32 v160, 16, v142
	v_and_b32_e32 v161, 0xffff0000, v142
	v_lshlrev_b32_e32 v162, 16, v143
	v_and_b32_e32 v163, 0xffff0000, v143
	v_pk_mul_f32 v[156:157], v[156:157], v[160:161]
	v_pk_mul_f32 v[158:159], v[158:159], v[162:163]
	s_nop 0
	v_cvt_pk_bf16_f32 v166, v156, v157
	v_cvt_pk_bf16_f32 v167, v158, v159
	flat_store_dwordx2 v[54:55], v[166:167] offset:16
	v_pk_add_f32 v[156:157], v[26:27], v[48:49] op_sel_hi:[1,0]
	v_pk_add_f32 v[158:159], v[28:29], v[48:49] op_sel_hi:[1,0]
	v_lshlrev_b32_e32 v160, 16, v144
	v_and_b32_e32 v161, 0xffff0000, v144
	v_lshlrev_b32_e32 v162, 16, v145
	v_and_b32_e32 v163, 0xffff0000, v145
	v_pk_mul_f32 v[156:157], v[156:157], v[160:161]
	v_pk_mul_f32 v[158:159], v[158:159], v[162:163]
	s_nop 0
	v_cvt_pk_bf16_f32 v164, v156, v157
	v_cvt_pk_bf16_f32 v165, v158, v159
	flat_store_dwordx2 v[54:55], v[164:165] offset:32
	v_pk_add_f32 v[156:157], v[30:31], v[48:49] op_sel_hi:[1,0]
	v_pk_add_f32 v[158:159], v[32:33], v[48:49] op_sel_hi:[1,0]
	v_lshlrev_b32_e32 v160, 16, v146
	v_and_b32_e32 v161, 0xffff0000, v146
	v_lshlrev_b32_e32 v162, 16, v147
	v_and_b32_e32 v163, 0xffff0000, v147
	v_pk_mul_f32 v[156:157], v[156:157], v[160:161]
	v_pk_mul_f32 v[158:159], v[158:159], v[162:163]
	s_nop 0
	v_cvt_pk_bf16_f32 v166, v156, v157
	v_cvt_pk_bf16_f32 v167, v158, v159
	flat_store_dwordx2 v[54:55], v[166:167] offset:48
	v_pk_add_f32 v[156:157], v[48:49], v[2:3] op_sel_hi:[0,1]
	v_pk_add_f32 v[158:159], v[48:49], v[4:5] op_sel_hi:[0,1]
	v_lshlrev_b32_e32 v160, 16, v148
	v_and_b32_e32 v161, 0xffff0000, v148
	v_lshlrev_b32_e32 v162, 16, v149
	v_and_b32_e32 v163, 0xffff0000, v149
	v_pk_mul_f32 v[156:157], v[156:157], v[160:161]
	v_pk_mul_f32 v[158:159], v[158:159], v[162:163]
	s_nop 0
	v_cvt_pk_bf16_f32 v164, v156, v157
	v_cvt_pk_bf16_f32 v165, v158, v159
	flat_store_dwordx2 v[138:139], v[164:165]
	v_pk_add_f32 v[156:157], v[48:49], v[6:7] op_sel_hi:[0,1]
	v_pk_add_f32 v[158:159], v[48:49], v[8:9] op_sel_hi:[0,1]
	v_lshlrev_b32_e32 v160, 16, v150
	v_and_b32_e32 v161, 0xffff0000, v150
	v_lshlrev_b32_e32 v162, 16, v151
	v_and_b32_e32 v163, 0xffff0000, v151
	v_pk_mul_f32 v[156:157], v[156:157], v[160:161]
	v_pk_mul_f32 v[158:159], v[158:159], v[162:163]
	s_nop 0
	v_cvt_pk_bf16_f32 v166, v156, v157
	v_cvt_pk_bf16_f32 v167, v158, v159
	flat_store_dwordx2 v[138:139], v[166:167] offset:16
	v_pk_add_f32 v[156:157], v[48:49], v[10:11] op_sel_hi:[0,1]
	v_pk_add_f32 v[158:159], v[48:49], v[12:13] op_sel_hi:[0,1]
	v_lshlrev_b32_e32 v160, 16, v152
	v_and_b32_e32 v161, 0xffff0000, v152
	v_lshlrev_b32_e32 v162, 16, v153
	v_and_b32_e32 v163, 0xffff0000, v153
	v_pk_mul_f32 v[156:157], v[156:157], v[160:161]
	v_pk_mul_f32 v[158:159], v[158:159], v[162:163]
	s_nop 0
	v_cvt_pk_bf16_f32 v164, v156, v157
	v_cvt_pk_bf16_f32 v165, v158, v159
	flat_store_dwordx2 v[138:139], v[164:165] offset:32
	v_pk_add_f32 v[156:157], v[48:49], v[14:15] op_sel_hi:[0,1]
	v_pk_add_f32 v[158:159], v[48:49], v[16:17] op_sel_hi:[0,1]
	v_lshlrev_b32_e32 v160, 16, v154
	v_and_b32_e32 v161, 0xffff0000, v154
	v_lshlrev_b32_e32 v162, 16, v155
	v_and_b32_e32 v163, 0xffff0000, v155
	v_pk_mul_f32 v[156:157], v[156:157], v[160:161]
	v_pk_mul_f32 v[158:159], v[158:159], v[162:163]
	s_nop 0
	v_cvt_pk_bf16_f32 v166, v156, v157
	v_cvt_pk_bf16_f32 v167, v158, v159
	flat_store_dwordx2 v[138:139], v[166:167] offset:48
